# MLA: step K/V LDS stores moved into the hot-path MFMA shadow (after 10th MFMA), on top of distance-2 prefetch
# speedup vs baseline: 1.0370x; 1.0048x over previous
; template <bool MLA, int DK, int DV>
; __device__ __forceinline__ void attn_core(const Params& p, int b, int h, int map, int q0, int nt, char* smem,
;                                           f32x16 (&o)[DV / 32], float& lout) {
;     ...
;     __syncthreads();
;   };
;   for (int kt = 0; kt < nt; kt += 2) {
;     step(kt, sc_cur, sc_nxt);
;     step(kt + 1, sc_nxt, sc_cur);
;   }
.Lmla2_post:
	s_add_i32 s68, s68, 2
	v_add_u32_e32 v158, 0x80, v158
	v_add_u32_e32 v154, 0x80, v154
	s_cmp_lt_u32 s78, s34
	v_lshl_add_u64 v[150:151], v[150:151], 0, s[4:5]
	s_waitcnt lgkmcnt(0)
	s_barrier
	s_cbranch_scc0 .LBB0_605

; template <bool MLA, int DK, int DV>
; __device__ __forceinline__ void attn_core(const Params& p, int b, int h, int map, int q0, int nt, char* smem,
;                                           f32x16 (&o)[DV / 32], float& lout) {
;     ...
;         for (int i = 0; i < 16; ++i) nxt_[sub][i] = 0.f;
;       constexpr int NM = 2 * NKS;
;       bf16x8 kf[NM];
; #pragma unroll
;       for (int j = 0; j < NM; ++j) kf[j] = *(const bf16x8*)(Kn + ((j / NKS) * 32 + r) * KS_STRIDE + (j % NKS) * 16 + h2 * 8);
; #pragma unroll
;       for (int j = 0; j < NM; ++j) {
;         nxt_[j / NKS] = MFMA32(kf[j], qf[j % NKS], nxt_[j / NKS]);
; #pragma unroll
;         for (int e_ = j * 32 / NM; e_ < (j + 1) * 32 / NM; ++e_) {
;           const float x_ = __builtin_amdgcn_exp2f(fmaf(cur_[e_ >> 4][e_ & 15], sc, -mrun));
;           cur_[e_ >> 4][e_ & 15] = x_; psum += x_;
;         }
;       }
;       __builtin_amdgcn_sched_group_barrier(0x100, NM, 0);
; #pragma unroll
;       for (int j = 0; j < NM; ++j) {
;         __builtin_amdgcn_sched_group_barrier(0x008, 1, 0);
;         __builtin_amdgcn_sched_group_barrier(0x002, 96 / NM, 0);
;       }
;     } else {
; #pragma unroll
;       for (int sub = 0; sub < 2; ++sub)
; #pragma unroll
;         for (int i = 0; i < 16; ++i) { const float x_ = __builtin_amdgcn_exp2f(fmaf(cur_[sub][i], sc, -mrun)); cur_[sub][i] = x_; psum += x_; }
;     }
;     lrun += psum;
;     bf16x8 pb[4];
; #pragma unroll
;     for (int kb = 0; kb < 4; ++kb) {
;       const int sub = kb >> 1, s8 = (kb & 1) * 8;
;       u32x4 pk;
;       pk.x = pack2(cur_[sub][s8 + 0], cur_[sub][s8 + 1]);
;       pk.y = pack2(cur_[sub][s8 + 2], cur_[sub][s8 + 3]);
;       pk.z = pack2(cur_[sub][s8 + 4], cur_[sub][s8 + 5]);
;       pk.w = pack2(cur_[sub][s8 + 6], cur_[sub][s8 + 7]);
;       pb[kb] = __builtin_bit_cast(bf16x8, pk);
;     }
;     float mx = -INFINITY;
; #pragma unroll
;     for (int hb = 0; hb < 2; ++hb) {
;       bf16x8 vf[2][NDVT];
; #pragma unroll
;       for (int q = 0; q < 2; ++q)
; #pragma unroll
;         for (int d = 0; d < NDVT; ++d) {
;           const bft* vp = Vc + (d * 32 + r) * VS_STRIDE + (hb * 2 + q) * 16 + 4 * h2;
;           const u32x2 lo = *(const u32x2*)vp, hi = *(const u32x2*)(vp + 8);
;           const u32x4 pa4 = {lo.x, lo.y, hi.x, hi.y};
;           vf[q][d] = __builtin_bit_cast(bf16x8, pa4);
;         }
; #pragma unroll
.LBB0_559:
	s_or_b64 exec, exec, s[74:75]
	s_and_b64 vcc, exec, s[76:77]
	s_cbranch_vccnz .Lmla1_cold
	ds_read_b128 v[132:135], v155 offset:13312
	ds_read_b128 v[136:139], v155 offset:13344
	ds_read_b128 v[198:201], v155 offset:13376
	ds_read_b128 v[202:205], v155 offset:13408
	ds_read_b128 v[248:251], v155 offset:13440
	ds_read_b128 v[216:219], v155 offset:13472
	v_add_u32_e32 v244, 0x6800, v157
	v_add_u32_e32 v245, 0x7800, v157
	v_exp_f32_e32 v16, v16
	v_exp_f32_e32 v17, v17
	v_exp_f32_e32 v18, v18
	v_exp_f32_e32 v19, v19
	v_add_f32_e32 v163, v16, v18
	v_add_f32_e32 v210, v17, v19
	s_waitcnt lgkmcnt(5)
	v_mfma_f32_32x32x16_bf16 v[48:63], v[132:135], v[96:99], v[164:179]
	ds_read_b128 v[132:135], v155 offset:19968
	v_exp_f32_e32 v20, v20
	v_exp_f32_e32 v21, v21
	v_exp_f32_e32 v22, v22
	s_waitcnt lgkmcnt(5)
	v_mfma_f32_32x32x16_bf16 v[48:63], v[136:139], v[100:103], v[48:63]
	ds_read_b128 v[136:139], v155 offset:20000
	v_exp_f32_e32 v23, v23
	v_add_f32_e32 v163, v20, v163
	v_add_f32_e32 v210, v21, v210
	s_waitcnt lgkmcnt(5)
	v_mfma_f32_32x32x16_bf16 v[48:63], v[198:201], v[104:107], v[48:63]
	ds_read_b128 v[198:201], v155 offset:20032
	v_add_f32_e32 v163, v22, v163
	v_add_f32_e32 v210, v23, v210
	v_cvt_pk_bf16_f32 v180, v16, v17
	v_cvt_pk_bf16_f32 v181, v18, v19
	v_cvt_pk_bf16_f32 v182, v20, v21
	s_waitcnt lgkmcnt(5)
	v_mfma_f32_32x32x16_bf16 v[48:63], v[202:205], v[108:111], v[48:63]
	ds_read_b128 v[202:205], v155 offset:20064
	v_cvt_pk_bf16_f32 v183, v22, v23
	v_exp_f32_e32 v24, v24
	v_exp_f32_e32 v25, v25
	s_waitcnt lgkmcnt(5)
	v_mfma_f32_32x32x16_bf16 v[48:63], v[248:251], v[112:115], v[48:63]
	ds_read_b128 v[248:251], v155 offset:20096
	v_exp_f32_e32 v26, v26
	v_exp_f32_e32 v27, v27
	v_add_f32_e32 v163, v24, v163
	s_waitcnt lgkmcnt(5)
	v_mfma_f32_32x32x16_bf16 v[48:63], v[216:219], v[116:119], v[48:63]
	ds_read_b128 v[216:219], v155 offset:20128
	v_add_f32_e32 v210, v25, v210
	v_add_f32_e32 v163, v26, v163
	v_add_f32_e32 v210, v27, v210
	v_exp_f32_e32 v28, v28
	s_waitcnt lgkmcnt(5)
	v_mfma_f32_32x32x16_bf16 v[80:95], v[132:135], v[96:99], v[164:179]
	ds_read2_b64 v[132:135], v244 offset0:0 offset1:2
	v_exp_f32_e32 v29, v29
	v_exp_f32_e32 v30, v30
	v_exp_f32_e32 v31, v31
	s_waitcnt lgkmcnt(5)
	v_mfma_f32_32x32x16_bf16 v[80:95], v[136:139], v[100:103], v[80:95]
	ds_read2_b64 v[136:139], v245 offset0:32 offset1:34
	v_add_f32_e32 v163, v28, v163
	v_add_f32_e32 v210, v29, v210
	v_add_f32_e32 v163, v30, v163
	v_add_f32_e32 v210, v31, v210
	s_waitcnt lgkmcnt(5)
	v_mfma_f32_32x32x16_bf16 v[80:95], v[198:201], v[104:107], v[80:95]
	ds_read2_b64 v[198:201], v244 offset0:4 offset1:6
	v_cvt_pk_bf16_f32 v184, v24, v25
	v_cvt_pk_bf16_f32 v185, v26, v27
	v_cvt_pk_bf16_f32 v186, v28, v29
	v_cvt_pk_bf16_f32 v187, v30, v31
	v_exp_f32_e32 v64, v64
	s_waitcnt lgkmcnt(5)
	v_mfma_f32_32x32x16_bf16 v[80:95], v[202:205], v[108:111], v[80:95]
	s_cmp_lt_u32 s68, s34
	s_cbranch_scc0 .Lm1i_ns
	s_and_b64 vcc, exec, s[8:9]
	s_cbranch_vccnz .Lm1i_w3
	s_waitcnt vmcnt(2)
	s_branch .Lm1i_wd

.Lm1i_wd:
	s_andn2_b64 vcc, exec, s[70:71]
	s_cbranch_vccnz .Lm1i_a
	s_and_saveexec_b64 s[74:75], s[6:7]
	s_cbranch_execz .Lm1i_b
	ds_write_b128 v159, v[124:127]

; DI unsigned pack2(float lo, float hi) { f2v_ f = {lo, hi}; b2v_ b = __builtin_convertvector(f, b2v_); return __builtin_bit_cast(unsigned, b); }
; #define MFMA32(a, b, c) __builtin_amdgcn_mfma_f32_32x32x16_bf16((a), (b), (c), 0, 0, 0)
; template <bool MLA, int DK, int DV>
; __device__ __forceinline__ void attn_core(const Params& p, int b, int h, int map, int q0, int nt, char* smem,
;                                           f32x16 (&o)[DV / 32], float& lout) {
;     ...
;     bf16x8 pb[4];
; #pragma unroll
;     for (int kb = 0; kb < 4; ++kb) {
;       const int sub = kb >> 1, s8 = (kb & 1) * 8;
;       u32x4 pk;
;       pk.x = pack2(cur_[sub][s8 + 0], cur_[sub][s8 + 1]);
;       pk.y = pack2(cur_[sub][s8 + 2], cur_[sub][s8 + 3]);
;       pk.z = pack2(cur_[sub][s8 + 4], cur_[sub][s8 + 5]);
;       pk.w = pack2(cur_[sub][s8 + 6], cur_[sub][s8 + 7]);
;       pb[kb] = __builtin_bit_cast(bf16x8, pk);
;     }
;     float mx = -INFINITY;
; #pragma unroll
;     for (int hb = 0; hb < 2; ++hb) {
;       bf16x8 vf[2][NDVT];
; #pragma unroll
;       for (int q = 0; q < 2; ++q)
; #pragma unroll
;         for (int d = 0; d < NDVT; ++d) {
;           const bft* vp = Vc + (d * 32 + r) * VS_STRIDE + (hb * 2 + q) * 16 + 4 * h2;
;           const u32x2 lo = *(const u32x2*)vp, hi = *(const u32x2*)(vp + 8);
;           const u32x4 pa4 = {lo.x, lo.y, hi.x, hi.y};
;           vf[q][d] = __builtin_bit_cast(bf16x8, pa4);
;         }
; #pragma unroll
;       for (int q = 0; q < 2; ++q) {
;         const int kb = hb * 2 + q;
; #pragma unroll
;         for (int d = 0; d < NDVT; ++d) o[d] = MFMA32(vf[q][d], pb[kb], o[d]);
; #pragma unroll
;         for (int i = 0; i < 8; ++i) mx = fmaxf(mx, nxt_[kb >> 1][(kb & 1) * 8 + i]);
;       }
;     }
;     if (has1) {
;       mx *= sc;
;       if (__any(mx > mrun + 12.f)) {
;         mx = fmaxf(mx, __shfl_xor(mx, 32));
;         const float mnew = fmaxf(mrun, mx);
;         const float alpha = __builtin_amdgcn_exp2f(mrun - mnew);
;         mrun = mnew;
;         lrun *= alpha;
; #pragma unroll
;         for (int d = 0; d < NDVT; ++d)
; #pragma unroll
;           for (int i = 0; i < 16; ++i) o[d][i] *= alpha;
;       }
.Lm1i_a:
	s_and_saveexec_b64 s[74:75], s[72:73]
	s_cbranch_execz .Lm1i_d
	v_add_u32_e32 v232, 0x8a00, v148
	ds_write2_b64 v232, v[120:121], v[122:123] offset1:1
.Lm1i_d:
	s_or_b64 exec, exec, s[74:75]
	s_nop 3
	ds_read2_b64 v[202:205], v245 offset0:36 offset1:38
	v_exp_f32_e32 v65, v65
	v_exp_f32_e32 v66, v66
	s_waitcnt lgkmcnt(5)
	v_mfma_f32_32x32x16_bf16 v[80:95], v[248:251], v[112:115], v[80:95]
	ds_read2_b64 v[248:251], v244 offset0:8 offset1:10
	v_exp_f32_e32 v67, v67
	v_add_f32_e32 v163, v64, v163
	v_add_f32_e32 v210, v65, v210
	s_waitcnt lgkmcnt(5)
	v_mfma_f32_32x32x16_bf16 v[80:95], v[216:219], v[116:119], v[80:95]
	ds_read2_b64 v[216:219], v245 offset0:40 offset1:42
	v_add_f32_e32 v163, v66, v163
	v_add_f32_e32 v210, v67, v210
	v_exp_f32_e32 v68, v68
	v_exp_f32_e32 v69, v69
	s_waitcnt lgkmcnt(5)
	v_mfma_f32_32x32x16_bf16 v[32:47], v[132:135], v[180:183], v[32:47]
	ds_read2_b64 v[132:135], v244 offset0:12 offset1:14
	v_exp_f32_e32 v70, v70
	v_exp_f32_e32 v71, v71
	s_waitcnt lgkmcnt(5)
	v_mfma_f32_32x32x16_bf16 v[0:15], v[136:139], v[180:183], v[0:15]
	ds_read2_b64 v[136:139], v245 offset0:44 offset1:46
	v_add_f32_e32 v163, v68, v163
	v_add_f32_e32 v210, v69, v210
	v_add_f32_e32 v163, v70, v163
	v_add_f32_e32 v210, v71, v210
	v_cvt_pk_bf16_f32 v188, v64, v65
	s_waitcnt lgkmcnt(5)
	v_mfma_f32_32x32x16_bf16 v[32:47], v[198:201], v[184:187], v[32:47]
	v_cvt_pk_bf16_f32 v189, v66, v67
	v_cvt_pk_bf16_f32 v190, v68, v69
	v_cvt_pk_bf16_f32 v191, v70, v71
	v_exp_f32_e32 v72, v72
	s_waitcnt lgkmcnt(4)
	v_mfma_f32_32x32x16_bf16 v[0:15], v[202:205], v[184:187], v[0:15]
	v_exp_f32_e32 v73, v73
	v_exp_f32_e32 v74, v74
	v_exp_f32_e32 v75, v75
	s_waitcnt lgkmcnt(3)
	v_mfma_f32_32x32x16_bf16 v[32:47], v[248:251], v[188:191], v[32:47]
	v_add_f32_e32 v163, v72, v163
	v_add_f32_e32 v210, v73, v210
	v_add_f32_e32 v163, v74, v163
	v_add_f32_e32 v210, v75, v210
	s_waitcnt lgkmcnt(2)
	v_mfma_f32_32x32x16_bf16 v[0:15], v[216:219], v[188:191], v[0:15]
	v_exp_f32_e32 v76, v76
	v_exp_f32_e32 v77, v77
	v_exp_f32_e32 v78, v78
	v_exp_f32_e32 v79, v79
	v_add_f32_e32 v163, v76, v163
	v_add_f32_e32 v210, v77, v210
	v_add_f32_e32 v163, v78, v163
	v_add_f32_e32 v210, v79, v210
	v_cvt_pk_bf16_f32 v192, v72, v73
	v_cvt_pk_bf16_f32 v193, v74, v75
	v_cvt_pk_bf16_f32 v194, v76, v77
	v_cvt_pk_bf16_f32 v195, v78, v79
	s_waitcnt lgkmcnt(1)
	s_nop 0
	v_mfma_f32_32x32x16_bf16 v[32:47], v[132:135], v[192:195], v[32:47]
	s_waitcnt lgkmcnt(0)
	v_mfma_f32_32x32x16_bf16 v[0:15], v[136:139], v[192:195], v[0:15]
	v_add_f32_e32 v163, v163, v210
	v_add_f32_e32 v149, v149, v163
	s_andn2_b64 s[16:17], exec, s[70:71]
	v_cmp_lt_f32_e32 vcc, 0x45800000, v163
	s_cbranch_vccz .Lmla1_post
	v_max3_f32 v163, v16, v17, v18
	v_max3_f32 v163, v163, v19, v20
	v_max3_f32 v163, v163, v21, v22
	v_max3_f32 v163, v163, v23, v24
	v_max3_f32 v163, v163, v25, v26
	v_max3_f32 v163, v163, v27, v28
	v_max3_f32 v163, v163, v29, v30
	v_max3_f32 v163, v163, v31, v64
	v_max3_f32 v163, v163, v65, v66
	v_max3_f32 v163, v163, v67, v68
	v_max3_f32 v163, v163, v69, v70
	v_max3_f32 v163, v163, v71, v72
	v_max3_f32 v163, v163, v73, v74
	v_max3_f32 v163, v163, v75, v76
	v_max3_f32 v163, v163, v77, v78
	v_max_f32_e32 v163, v163, v79
	ds_bpermute_b32 v210, v156, v163
	s_waitcnt lgkmcnt(0)
	v_max_f32_e32 v163, v163, v210
	v_frexp_exp_i32_f32_e32 v210, v163
	v_max_i32_e32 v210, 0, v210
	v_sub_u32_e32 v247, 0, v210
	v_ldexp_f32 v247, 1.0, v247
	v_cvt_f32_i32_e32 v210, v210
	v_mul_f32_e32 v149, v149, v247
	v_mul_f32_e32 v32, v32, v247
	v_mul_f32_e32 v33, v33, v247
	v_mul_f32_e32 v34, v34, v247
	v_mul_f32_e32 v35, v35, v247
	v_mul_f32_e32 v36, v36, v247
	v_mul_f32_e32 v37, v37, v247
	v_mul_f32_e32 v38, v38, v247
	v_mul_f32_e32 v39, v39, v247
	v_mul_f32_e32 v40, v40, v247
	v_mul_f32_e32 v41, v41, v247
	v_mul_f32_e32 v42, v42, v247
	v_mul_f32_e32 v43, v43, v247
	v_mul_f32_e32 v44, v44, v247
	v_mul_f32_e32 v45, v45, v247
	v_mul_f32_e32 v46, v46, v247
	v_mul_f32_e32 v47, v47, v247
	v_mul_f32_e32 v0, v0, v247
	v_mul_f32_e32 v1, v1, v247
	v_mul_f32_e32 v2, v2, v247
	v_mul_f32_e32 v3, v3, v247
	v_mul_f32_e32 v4, v4, v247
	v_mul_f32_e32 v5, v5, v247
	v_mul_f32_e32 v6, v6, v247
	v_mul_f32_e32 v7, v7, v247
	v_mul_f32_e32 v8, v8, v247
	v_mul_f32_e32 v9, v9, v247
	v_mul_f32_e32 v10, v10, v247
	v_mul_f32_e32 v11, v11, v247
	v_mul_f32_e32 v12, v12, v247
	v_mul_f32_e32 v13, v13, v247
	v_mul_f32_e32 v14, v14, v247
	v_mul_f32_e32 v15, v15, v247
	v_sub_f32_e32 v164, v164, v210
	v_sub_f32_e32 v165, v165, v210
	v_sub_f32_e32 v166, v166, v210
	v_sub_f32_e32 v167, v167, v210
	v_sub_f32_e32 v168, v168, v210
	v_sub_f32_e32 v169, v169, v210
	v_sub_f32_e32 v170, v170, v210
	v_sub_f32_e32 v171, v171, v210
	v_sub_f32_e32 v172, v172, v210
	v_sub_f32_e32 v173, v173, v210
	v_sub_f32_e32 v174, v174, v210
	v_sub_f32_e32 v175, v175, v210
	v_sub_f32_e32 v176, v176, v210
	v_sub_f32_e32 v177, v177, v210
	v_sub_f32_e32 v178, v178, v210
	v_sub_f32_e32 v179, v179, v210
	v_sub_f32_e32 v48, v48, v210
	v_sub_f32_e32 v49, v49, v210
	v_sub_f32_e32 v50, v50, v210
	v_sub_f32_e32 v51, v51, v210
	v_sub_f32_e32 v52, v52, v210
	v_sub_f32_e32 v53, v53, v210
	v_sub_f32_e32 v54, v54, v210
	v_sub_f32_e32 v55, v55, v210
	v_sub_f32_e32 v56, v56, v210
	v_sub_f32_e32 v57, v57, v210
	v_sub_f32_e32 v58, v58, v210
	v_sub_f32_e32 v59, v59, v210
	v_sub_f32_e32 v60, v60, v210
	v_sub_f32_e32 v61, v61, v210
	v_sub_f32_e32 v62, v62, v210
	v_sub_f32_e32 v63, v63, v210
	v_sub_f32_e32 v80, v80, v210
	v_sub_f32_e32 v81, v81, v210
	v_sub_f32_e32 v82, v82, v210
	v_sub_f32_e32 v83, v83, v210
	v_sub_f32_e32 v84, v84, v210
	v_sub_f32_e32 v85, v85, v210
	v_sub_f32_e32 v86, v86, v210
	v_sub_f32_e32 v87, v87, v210
	v_sub_f32_e32 v88, v88, v210
	v_sub_f32_e32 v89, v89, v210
	v_sub_f32_e32 v90, v90, v210
	v_sub_f32_e32 v91, v91, v210
	v_sub_f32_e32 v92, v92, v210
	v_sub_f32_e32 v93, v93, v210
	v_sub_f32_e32 v94, v94, v210
	v_sub_f32_e32 v95, v95, v210
	v_add_f32_e32 v162, v162, v210
	s_branch .Lmla1_post

; template <bool MLA, int DK, int DV>
; __device__ __forceinline__ void attn_core(const Params& p, int b, int h, int map, int q0, int nt, char* smem,
;                                           f32x16 (&o)[DV / 32], float& lout) {
;     ...
;     if (has2) ATTN_STOREK(kt & 1);
;     if (has1) ATTN_STOREV((kt + 1) & 1);
;     __syncthreads();
.Lmla1_post:
	s_cmp_lt_u32 s68, s34
	s_cselect_b64 s[72:73], -1, 0
	s_add_i32 s60, s68, 1
	s_cmp_ge_u32 s60, s34
	s_waitcnt lgkmcnt(0)
	s_barrier
	s_cbranch_scc1 .LBB0_588
	s_and_saveexec_b64 s[74:75], s[6:7]
	s_cbranch_execz .Lm2k_c0
	v_add_u32_e32 v124, s38, v158
	v_add_u32_e32 v126, 0x100, v124
	v_ashrrev_i32_e32 v127, 31, v126
	s_and_saveexec_b64 s[76:77], s[12:13]
	s_xor_b64 s[76:77], exec, s[76:77]
	v_lshlrev_b64 v[124:125], 6, v[126:127]
	s_movk_i32 s60, 0xff80
	v_lshl_add_u64 v[124:125], v[140:141], 0, v[124:125]
	s_mov_b32 s61, -1
	v_lshl_add_u64 v[124:125], v[124:125], 0, s[60:61]
	s_andn2_saveexec_b64 s[76:77], s[76:77]
	v_mad_i64_i32 v[124:125], s[80:81], v126, s1, v[142:143]
	s_or_b64 exec, exec, s[76:77]
	global_load_dwordx4 v[124:127], v[124:125], off

; template <bool MLA, int DK, int DV>
; __device__ __forceinline__ void attn_core(const Params& p, int b, int h, int map, int q0, int nt, char* smem,
;                                           f32x16 (&o)[DV / 32], float& lout) {
;     ...
;         for (int i = 0; i < 16; ++i) nxt_[sub][i] = 0.f;
;       constexpr int NM = 2 * NKS;
;       bf16x8 kf[NM];
; #pragma unroll
;       for (int j = 0; j < NM; ++j) kf[j] = *(const bf16x8*)(Kn + ((j / NKS) * 32 + r) * KS_STRIDE + (j % NKS) * 16 + h2 * 8);
; #pragma unroll
;       for (int j = 0; j < NM; ++j) {
;         nxt_[j / NKS] = MFMA32(kf[j], qf[j % NKS], nxt_[j / NKS]);
; #pragma unroll
;         for (int e_ = j * 32 / NM; e_ < (j + 1) * 32 / NM; ++e_) {
;           const float x_ = __builtin_amdgcn_exp2f(fmaf(cur_[e_ >> 4][e_ & 15], sc, -mrun));
;           cur_[e_ >> 4][e_ & 15] = x_; psum += x_;
;         }
;       }
;       __builtin_amdgcn_sched_group_barrier(0x100, NM, 0);
; #pragma unroll
;       for (int j = 0; j < NM; ++j) {
;         __builtin_amdgcn_sched_group_barrier(0x008, 1, 0);
;         __builtin_amdgcn_sched_group_barrier(0x002, 96 / NM, 0);
;       }
;     } else {
; #pragma unroll
;       for (int sub = 0; sub < 2; ++sub)
; #pragma unroll
;         for (int i = 0; i < 16; ++i) { const float x_ = __builtin_amdgcn_exp2f(fmaf(cur_[sub][i], sc, -mrun)); cur_[sub][i] = x_; psum += x_; }
;     }
;     lrun += psum;
;     bf16x8 pb[4];
; #pragma unroll
;     for (int kb = 0; kb < 4; ++kb) {
;       const int sub = kb >> 1, s8 = (kb & 1) * 8;
;       u32x4 pk;
;       pk.x = pack2(cur_[sub][s8 + 0], cur_[sub][s8 + 1]);
;       pk.y = pack2(cur_[sub][s8 + 2], cur_[sub][s8 + 3]);
;       pk.z = pack2(cur_[sub][s8 + 4], cur_[sub][s8 + 5]);
;       pk.w = pack2(cur_[sub][s8 + 6], cur_[sub][s8 + 7]);
;       pb[kb] = __builtin_bit_cast(bf16x8, pk);
;     }
;     float mx = -INFINITY;
; #pragma unroll
;     for (int hb = 0; hb < 2; ++hb) {
;       bf16x8 vf[2][NDVT];
; #pragma unroll
;       for (int q = 0; q < 2; ++q)
; #pragma unroll
;         for (int d = 0; d < NDVT; ++d) {
;           const bft* vp = Vc + (d * 32 + r) * VS_STRIDE + (hb * 2 + q) * 16 + 4 * h2;
;           const u32x2 lo = *(const u32x2*)vp, hi = *(const u32x2*)(vp + 8);
;           const u32x4 pa4 = {lo.x, lo.y, hi.x, hi.y};
;           vf[q][d] = __builtin_bit_cast(bf16x8, pa4);
;         }
; #pragma unroll
.LBB0_590:
	s_or_b64 exec, exec, s[74:75]
	s_and_b64 vcc, exec, s[50:51]
	s_cbranch_vccnz .Lmla2_cold
	ds_read_b128 v[132:135], v155 offset:0
	ds_read_b128 v[136:139], v155 offset:32
	ds_read_b128 v[198:201], v155 offset:64
	ds_read_b128 v[202:205], v155 offset:96
	ds_read_b128 v[248:251], v155 offset:128
	ds_read_b128 v[216:219], v155 offset:160
	v_add_u32_e32 v244, 0x8800, v157
	v_add_u32_e32 v245, 0x9800, v157
	v_exp_f32_e32 v48, v48
	v_exp_f32_e32 v49, v49
	v_exp_f32_e32 v50, v50
	v_exp_f32_e32 v51, v51
	v_add_f32_e32 v163, v48, v50
	v_add_f32_e32 v210, v49, v51
	s_waitcnt lgkmcnt(5)
	v_mfma_f32_32x32x16_bf16 v[16:31], v[132:135], v[96:99], v[164:179]
	ds_read_b128 v[132:135], v155 offset:6656
	v_exp_f32_e32 v52, v52
	v_exp_f32_e32 v53, v53
	v_exp_f32_e32 v54, v54
	s_waitcnt lgkmcnt(5)
	v_mfma_f32_32x32x16_bf16 v[16:31], v[136:139], v[100:103], v[16:31]
	ds_read_b128 v[136:139], v155 offset:6688
	v_exp_f32_e32 v55, v55
	v_add_f32_e32 v163, v52, v163
	v_add_f32_e32 v210, v53, v210
	s_waitcnt lgkmcnt(5)
	v_mfma_f32_32x32x16_bf16 v[16:31], v[198:201], v[104:107], v[16:31]
	ds_read_b128 v[198:201], v155 offset:6720
	v_add_f32_e32 v163, v54, v163
	v_add_f32_e32 v210, v55, v210
	v_cvt_pk_bf16_f32 v180, v48, v49
	v_cvt_pk_bf16_f32 v181, v50, v51
	v_cvt_pk_bf16_f32 v182, v52, v53
	s_waitcnt lgkmcnt(5)
	v_mfma_f32_32x32x16_bf16 v[16:31], v[202:205], v[108:111], v[16:31]
	ds_read_b128 v[202:205], v155 offset:6752
	v_cvt_pk_bf16_f32 v183, v54, v55
	v_exp_f32_e32 v56, v56
	v_exp_f32_e32 v57, v57
	s_waitcnt lgkmcnt(5)
	v_mfma_f32_32x32x16_bf16 v[16:31], v[248:251], v[112:115], v[16:31]
	ds_read_b128 v[248:251], v155 offset:6784
	v_exp_f32_e32 v58, v58
	v_exp_f32_e32 v59, v59
	v_add_f32_e32 v163, v56, v163
	s_waitcnt lgkmcnt(5)
	v_mfma_f32_32x32x16_bf16 v[16:31], v[216:219], v[116:119], v[16:31]
	ds_read_b128 v[216:219], v155 offset:6816
	v_add_f32_e32 v210, v57, v210
	v_add_f32_e32 v163, v58, v163
	v_add_f32_e32 v210, v59, v210
	v_exp_f32_e32 v60, v60
	s_waitcnt lgkmcnt(5)
	v_mfma_f32_32x32x16_bf16 v[64:79], v[132:135], v[96:99], v[164:179]
	ds_read2_b64 v[132:135], v244 offset0:64 offset1:66
	v_exp_f32_e32 v61, v61
	v_exp_f32_e32 v62, v62
	v_exp_f32_e32 v63, v63
	s_waitcnt lgkmcnt(5)
	v_mfma_f32_32x32x16_bf16 v[64:79], v[136:139], v[100:103], v[64:79]
	ds_read2_b64 v[136:139], v245 offset0:96 offset1:98
	v_add_f32_e32 v163, v60, v163
	v_add_f32_e32 v210, v61, v210
	v_add_f32_e32 v163, v62, v163
	v_add_f32_e32 v210, v63, v210
	s_waitcnt lgkmcnt(5)
	v_mfma_f32_32x32x16_bf16 v[64:79], v[198:201], v[104:107], v[64:79]
	ds_read2_b64 v[198:201], v244 offset0:68 offset1:70
	v_cvt_pk_bf16_f32 v184, v56, v57
	v_cvt_pk_bf16_f32 v185, v58, v59
	v_cvt_pk_bf16_f32 v186, v60, v61
	v_cvt_pk_bf16_f32 v187, v62, v63
	v_exp_f32_e32 v80, v80
	s_waitcnt lgkmcnt(5)
	v_mfma_f32_32x32x16_bf16 v[64:79], v[202:205], v[108:111], v[64:79]
	s_add_i32 s60, s68, 1
	s_cmp_lt_u32 s60, s34
	s_cbranch_scc0 .Lm2i_ns
	s_and_b64 vcc, exec, s[8:9]
	s_cbranch_vccnz .Lm2i_w3
	s_waitcnt vmcnt(2)
	s_branch .Lm2i_wd

.Lm2i_wd:
	s_andn2_b64 vcc, exec, s[72:73]
	s_cbranch_vccnz .Lm2i_a
	s_and_saveexec_b64 s[74:75], s[6:7]
	s_cbranch_execz .Lm2i_b
	ds_write_b128 v159, v[220:223] offset:13312
.Lm2i_b:
	s_or_b64 exec, exec, s[74:75]
	s_and_saveexec_b64 s[74:75], s[8:9]
	s_cbranch_execz .Lm2i_c
	ds_write_b128 v160, v[224:227] offset:13312

; DI unsigned pack2(float lo, float hi) { f2v_ f = {lo, hi}; b2v_ b = __builtin_convertvector(f, b2v_); return __builtin_bit_cast(unsigned, b); }
; #define MFMA32(a, b, c) __builtin_amdgcn_mfma_f32_32x32x16_bf16((a), (b), (c), 0, 0, 0)
; template <bool MLA, int DK, int DV>
; __device__ __forceinline__ void attn_core(const Params& p, int b, int h, int map, int q0, int nt, char* smem,
;                                           f32x16 (&o)[DV / 32], float& lout) {
;     ...
;     bf16x8 pb[4];
; #pragma unroll
;     for (int kb = 0; kb < 4; ++kb) {
;       const int sub = kb >> 1, s8 = (kb & 1) * 8;
;       u32x4 pk;
;       pk.x = pack2(cur_[sub][s8 + 0], cur_[sub][s8 + 1]);
;       pk.y = pack2(cur_[sub][s8 + 2], cur_[sub][s8 + 3]);
;       pk.z = pack2(cur_[sub][s8 + 4], cur_[sub][s8 + 5]);
;       pk.w = pack2(cur_[sub][s8 + 6], cur_[sub][s8 + 7]);
;       pb[kb] = __builtin_bit_cast(bf16x8, pk);
;     }
;     float mx = -INFINITY;
; #pragma unroll
;     for (int hb = 0; hb < 2; ++hb) {
;       bf16x8 vf[2][NDVT];
; #pragma unroll
;       for (int q = 0; q < 2; ++q)
; #pragma unroll
;         for (int d = 0; d < NDVT; ++d) {
;           const bft* vp = Vc + (d * 32 + r) * VS_STRIDE + (hb * 2 + q) * 16 + 4 * h2;
;           const u32x2 lo = *(const u32x2*)vp, hi = *(const u32x2*)(vp + 8);
;           const u32x4 pa4 = {lo.x, lo.y, hi.x, hi.y};
;           vf[q][d] = __builtin_bit_cast(bf16x8, pa4);
;         }
; #pragma unroll
;       for (int q = 0; q < 2; ++q) {
;         const int kb = hb * 2 + q;
; #pragma unroll
;         for (int d = 0; d < NDVT; ++d) o[d] = MFMA32(vf[q][d], pb[kb], o[d]);
; #pragma unroll
;         for (int i = 0; i < 8; ++i) mx = fmaxf(mx, nxt_[kb >> 1][(kb & 1) * 8 + i]);
;       }
;     }
;     if (has1) {
;       mx *= sc;
;       if (__any(mx > mrun + 12.f)) {
;         mx = fmaxf(mx, __shfl_xor(mx, 32));
;         const float mnew = fmaxf(mrun, mx);
;         const float alpha = __builtin_amdgcn_exp2f(mrun - mnew);
;         mrun = mnew;
;         lrun *= alpha;
; #pragma unroll
;         for (int d = 0; d < NDVT; ++d)
; #pragma unroll
;           for (int i = 0; i < 16; ++i) o[d][i] *= alpha;
;       }
.Lm2i_a:
	s_and_saveexec_b64 s[74:75], s[70:71]
	s_cbranch_execz .Lm2i_d
	v_add_u32_e32 v232, 0x6800, v148
	ds_write2_b64 v232, v[228:229], v[230:231] offset1:1
.Lm2i_d:
	s_or_b64 exec, exec, s[74:75]
	s_nop 3
	ds_read2_b64 v[202:205], v245 offset0:100 offset1:102
	v_exp_f32_e32 v81, v81
	v_exp_f32_e32 v82, v82
	s_waitcnt lgkmcnt(5)
	v_mfma_f32_32x32x16_bf16 v[64:79], v[248:251], v[112:115], v[64:79]
	ds_read2_b64 v[248:251], v244 offset0:72 offset1:74
	v_exp_f32_e32 v83, v83
	v_add_f32_e32 v163, v80, v163
	v_add_f32_e32 v210, v81, v210
	s_waitcnt lgkmcnt(5)
	v_mfma_f32_32x32x16_bf16 v[64:79], v[216:219], v[116:119], v[64:79]
	ds_read2_b64 v[216:219], v245 offset0:104 offset1:106
	v_add_f32_e32 v163, v82, v163
	v_add_f32_e32 v210, v83, v210
	v_exp_f32_e32 v84, v84
	v_exp_f32_e32 v85, v85
	s_waitcnt lgkmcnt(5)
	v_mfma_f32_32x32x16_bf16 v[32:47], v[132:135], v[180:183], v[32:47]
	ds_read2_b64 v[132:135], v244 offset0:76 offset1:78
	v_exp_f32_e32 v86, v86
	v_exp_f32_e32 v87, v87
	s_waitcnt lgkmcnt(5)
	v_mfma_f32_32x32x16_bf16 v[0:15], v[136:139], v[180:183], v[0:15]
	ds_read2_b64 v[136:139], v245 offset0:108 offset1:110
	v_add_f32_e32 v163, v84, v163
	v_add_f32_e32 v210, v85, v210
	v_add_f32_e32 v163, v86, v163
	v_add_f32_e32 v210, v87, v210
	v_cvt_pk_bf16_f32 v188, v80, v81
	s_waitcnt lgkmcnt(5)
	v_mfma_f32_32x32x16_bf16 v[32:47], v[198:201], v[184:187], v[32:47]
	v_cvt_pk_bf16_f32 v189, v82, v83
	v_cvt_pk_bf16_f32 v190, v84, v85
	v_cvt_pk_bf16_f32 v191, v86, v87
	v_exp_f32_e32 v88, v88
	s_waitcnt lgkmcnt(4)
	v_mfma_f32_32x32x16_bf16 v[0:15], v[202:205], v[184:187], v[0:15]
	v_exp_f32_e32 v89, v89
	v_exp_f32_e32 v90, v90
	v_exp_f32_e32 v91, v91
	s_waitcnt lgkmcnt(3)
	v_mfma_f32_32x32x16_bf16 v[32:47], v[248:251], v[188:191], v[32:47]
	v_add_f32_e32 v163, v88, v163
	v_add_f32_e32 v210, v89, v210
	v_add_f32_e32 v163, v90, v163
	v_add_f32_e32 v210, v91, v210
	s_waitcnt lgkmcnt(2)
	v_mfma_f32_32x32x16_bf16 v[0:15], v[216:219], v[188:191], v[0:15]
	v_exp_f32_e32 v92, v92
	v_exp_f32_e32 v93, v93
	v_exp_f32_e32 v94, v94
	v_exp_f32_e32 v95, v95
	v_add_f32_e32 v163, v92, v163
	v_add_f32_e32 v210, v93, v210
	v_add_f32_e32 v163, v94, v163
	v_add_f32_e32 v210, v95, v210
	v_cvt_pk_bf16_f32 v192, v88, v89
	v_cvt_pk_bf16_f32 v193, v90, v91
	v_cvt_pk_bf16_f32 v194, v92, v93
	v_cvt_pk_bf16_f32 v195, v94, v95
	s_waitcnt lgkmcnt(1)
	s_nop 0
	v_mfma_f32_32x32x16_bf16 v[32:47], v[132:135], v[192:195], v[32:47]
	s_waitcnt lgkmcnt(0)
	v_mfma_f32_32x32x16_bf16 v[0:15], v[136:139], v[192:195], v[0:15]
	v_add_f32_e32 v163, v163, v210
	v_add_f32_e32 v149, v149, v163
	v_cmp_lt_f32_e32 vcc, 0x45800000, v163
	s_cbranch_vccz .Lmla2_post
	v_max3_f32 v163, v48, v49, v50
	v_max3_f32 v163, v163, v51, v52
	v_max3_f32 v163, v163, v53, v54
	v_max3_f32 v163, v163, v55, v56
	v_max3_f32 v163, v163, v57, v58
	v_max3_f32 v163, v163, v59, v60
	v_max3_f32 v163, v163, v61, v62
	v_max3_f32 v163, v163, v63, v80
	v_max3_f32 v163, v163, v81, v82
	v_max3_f32 v163, v163, v83, v84
	v_max3_f32 v163, v163, v85, v86
	v_max3_f32 v163, v163, v87, v88
	v_max3_f32 v163, v163, v89, v90
	v_max3_f32 v163, v163, v91, v92
	v_max3_f32 v163, v163, v93, v94
	v_max_f32_e32 v163, v163, v95
	ds_bpermute_b32 v210, v156, v163
	s_waitcnt lgkmcnt(0)
	v_max_f32_e32 v163, v163, v210
	v_frexp_exp_i32_f32_e32 v210, v163
	v_max_i32_e32 v210, 0, v210
	v_sub_u32_e32 v247, 0, v210
	v_ldexp_f32 v247, 1.0, v247
	v_cvt_f32_i32_e32 v210, v210
	v_mul_f32_e32 v149, v149, v247
	v_mul_f32_e32 v32, v32, v247
	v_mul_f32_e32 v33, v33, v247
	v_mul_f32_e32 v34, v34, v247
	v_mul_f32_e32 v35, v35, v247
	v_mul_f32_e32 v36, v36, v247
	v_mul_f32_e32 v37, v37, v247
	v_mul_f32_e32 v38, v38, v247
	v_mul_f32_e32 v39, v39, v247
	v_mul_f32_e32 v40, v40, v247
	v_mul_f32_e32 v41, v41, v247
	v_mul_f32_e32 v42, v42, v247
	v_mul_f32_e32 v43, v43, v247
	v_mul_f32_e32 v44, v44, v247
	v_mul_f32_e32 v45, v45, v247
	v_mul_f32_e32 v46, v46, v247
	v_mul_f32_e32 v47, v47, v247
	v_mul_f32_e32 v0, v0, v247
	v_mul_f32_e32 v1, v1, v247
	v_mul_f32_e32 v2, v2, v247
	v_mul_f32_e32 v3, v3, v247
	v_mul_f32_e32 v4, v4, v247
	v_mul_f32_e32 v5, v5, v247
	v_mul_f32_e32 v6, v6, v247
	v_mul_f32_e32 v7, v7, v247
	v_mul_f32_e32 v8, v8, v247
	v_mul_f32_e32 v9, v9, v247
	v_mul_f32_e32 v10, v10, v247
	v_mul_f32_e32 v11, v11, v247
	v_mul_f32_e32 v12, v12, v247
	v_mul_f32_e32 v13, v13, v247
	v_mul_f32_e32 v14, v14, v247
	v_mul_f32_e32 v15, v15, v247
	v_sub_f32_e32 v164, v164, v210
	v_sub_f32_e32 v165, v165, v210
	v_sub_f32_e32 v166, v166, v210
	v_sub_f32_e32 v167, v167, v210
	v_sub_f32_e32 v168, v168, v210
	v_sub_f32_e32 v169, v169, v210
	v_sub_f32_e32 v170, v170, v210
	v_sub_f32_e32 v171, v171, v210
	v_sub_f32_e32 v172, v172, v210
	v_sub_f32_e32 v173, v173, v210
	v_sub_f32_e32 v174, v174, v210
	v_sub_f32_e32 v175, v175, v210
	v_sub_f32_e32 v176, v176, v210
	v_sub_f32_e32 v177, v177, v210
	v_sub_f32_e32 v178, v178, v210
	v_sub_f32_e32 v179, v179, v210
	v_sub_f32_e32 v16, v16, v210
	v_sub_f32_e32 v17, v17, v210
	v_sub_f32_e32 v18, v18, v210
	v_sub_f32_e32 v19, v19, v210
	v_sub_f32_e32 v20, v20, v210
	v_sub_f32_e32 v21, v21, v210
	v_sub_f32_e32 v22, v22, v210
	v_sub_f32_e32 v23, v23, v210
	v_sub_f32_e32 v24, v24, v210
	v_sub_f32_e32 v25, v25, v210
	v_sub_f32_e32 v26, v26, v210
	v_sub_f32_e32 v27, v27, v210
	v_sub_f32_e32 v28, v28, v210
	v_sub_f32_e32 v29, v29, v210
	v_sub_f32_e32 v30, v30, v210
	v_sub_f32_e32 v31, v31, v210
	v_sub_f32_e32 v64, v64, v210
	v_sub_f32_e32 v65, v65, v210
	v_sub_f32_e32 v66, v66, v210
	v_sub_f32_e32 v67, v67, v210
	v_sub_f32_e32 v68, v68, v210
	v_sub_f32_e32 v69, v69, v210
	v_sub_f32_e32 v70, v70, v210
	v_sub_f32_e32 v71, v71, v210
	v_sub_f32_e32 v72, v72, v210
	v_sub_f32_e32 v73, v73, v210
	v_sub_f32_e32 v74, v74, v210
	v_sub_f32_e32 v75, v75, v210
	v_sub_f32_e32 v76, v76, v210
	v_sub_f32_e32 v77, v77, v210
	v_sub_f32_e32 v78, v78, v210
	v_sub_f32_e32 v79, v79, v210
	v_add_f32_e32 v162, v162, v210
	s_branch .Lmla2_post
